# attention P.V: V-fragment LDS reads run 3 MFMAs ahead instead of 6 (fewer LDS reads in flight per wave)
# speedup vs baseline: 1.0089x; 1.0031x over previous
.LBB0_679:
	s_cmp_ge_u32 s75, s72
	s_cbranch_scc1 .Lattn_pv_nodma
	v_lshl_add_u32 v227, s36, 15, v230
	s_mov_b32 s37, m0
	s_xor_b32 s6, s36, 1
	s_lshl_b32 s7, s6, 14
	s_add_i32 s7, s7, s69
	s_lshl_b32 s6, s6, 15
	s_add_i32 s6, s6, s70
	ds_read_b64_tr_b16 v[114:115], v227 offset:32768
	ds_read_b64_tr_b16 v[116:117], v227 offset:33280
	ds_read_b64_tr_b16 v[118:119], v227 offset:33792
	ds_read_b64_tr_b16 v[120:121], v227 offset:34304
	ds_read_b64_tr_b16 v[122:123], v227 offset:34816
	ds_read_b64_tr_b16 v[124:125], v227 offset:35328
	v_exp_f32_e32 v146, v146
	v_exp_f32_e32 v147, v147
	v_exp_f32_e32 v162, v162
	v_exp_f32_e32 v163, v163
	v_exp_f32_e32 v148, v148
	v_exp_f32_e32 v149, v149
	v_exp_f32_e32 v164, v164
	v_exp_f32_e32 v165, v165
	v_cvt_pk_bf16_f32 v82, v146, v147
	v_cvt_pk_bf16_f32 v90, v162, v163
	v_exp_f32_e32 v150, v150
	v_exp_f32_e32 v151, v151
	v_exp_f32_e32 v166, v166
	v_exp_f32_e32 v167, v167
	v_cvt_pk_bf16_f32 v83, v148, v149
	v_cvt_pk_bf16_f32 v91, v164, v165
	v_exp_f32_e32 v152, v152
	v_exp_f32_e32 v153, v153
	v_exp_f32_e32 v168, v168
	v_exp_f32_e32 v169, v169
	v_cvt_pk_bf16_f32 v84, v150, v151
	v_cvt_pk_bf16_f32 v92, v166, v167
	v_exp_f32_e32 v154, v154
	v_exp_f32_e32 v155, v155
	v_exp_f32_e32 v170, v170
	v_exp_f32_e32 v171, v171
	v_cvt_pk_bf16_f32 v85, v152, v153
	v_cvt_pk_bf16_f32 v93, v168, v169
	v_exp_f32_e32 v156, v156
	v_exp_f32_e32 v157, v157
	v_exp_f32_e32 v172, v172
	v_exp_f32_e32 v173, v173
	v_cvt_pk_bf16_f32 v86, v154, v155
	v_cvt_pk_bf16_f32 v94, v170, v171
	v_exp_f32_e32 v158, v158
	v_exp_f32_e32 v159, v159
	v_exp_f32_e32 v174, v174
	v_exp_f32_e32 v175, v175
	v_cvt_pk_bf16_f32 v87, v156, v157
	v_cvt_pk_bf16_f32 v95, v172, v173
	v_exp_f32_e32 v160, v160
	v_exp_f32_e32 v161, v161
	v_exp_f32_e32 v176, v176
	v_exp_f32_e32 v177, v177
	v_cvt_pk_bf16_f32 v88, v158, v159
	v_cvt_pk_bf16_f32 v96, v174, v175
	s_nop 0
	v_cvt_pk_bf16_f32 v89, v160, v161
	v_cvt_pk_bf16_f32 v97, v176, v177
	s_waitcnt lgkmcnt(4)
	v_mfma_f32_32x32x16_bf16 v[50:65], v[82:85], v[114:117], v[50:65]
	ds_read_b64_tr_b16 v[126:127], v227 offset:35840
	ds_read_b64_tr_b16 v[128:129], v227 offset:36352
	v_exp_f32_e32 v178, v178
	v_exp_f32_e32 v179, v179
	s_waitcnt lgkmcnt(4)
	v_mfma_f32_32x32x16_bf16 v[50:65], v[86:89], v[118:121], v[50:65]
	ds_read_b64_tr_b16 v[130:131], v227 offset:36864
	ds_read_b64_tr_b16 v[132:133], v227 offset:37376
	s_add_u32 s58, s56, 0x60000
	s_addc_u32 s59, s57, 0
	v_lshl_add_u64 v[228:229], v[238:239], 0, s[58:59]
	s_add_i32 m0, s7, 0x2000
	s_nop 0
	global_load_lds_dwordx4 v[228:229], off
	v_exp_f32_e32 v180, v180
	v_exp_f32_e32 v181, v181
	v_cvt_pk_bf16_f32 v98, v178, v179
	s_waitcnt lgkmcnt(4)
	v_mfma_f32_32x32x16_bf16 v[50:65], v[90:93], v[122:125], v[50:65]
	ds_read_b64_tr_b16 v[134:135], v227 offset:37888
	ds_read_b64_tr_b16 v[136:137], v227 offset:38400
	v_exp_f32_e32 v182, v182
	v_exp_f32_e32 v183, v183
	v_cvt_pk_bf16_f32 v99, v180, v181
	s_waitcnt lgkmcnt(4)
	v_mfma_f32_32x32x16_bf16 v[50:65], v[94:97], v[126:129], v[50:65]
	ds_read_b64_tr_b16 v[138:139], v227 offset:38912
	ds_read_b64_tr_b16 v[140:141], v227 offset:39424
	s_add_u32 s58, s56, 0x20060000
	s_addc_u32 s59, s57, 0
	v_lshl_add_u64 v[228:229], v[240:241], 0, s[58:59]
	s_add_i32 m0, s6, 0x4000
	s_nop 0
	global_load_lds_dwordx4 v[228:229], off
	v_exp_f32_e32 v184, v184
	v_exp_f32_e32 v185, v185
	v_cvt_pk_bf16_f32 v100, v182, v183
	s_waitcnt lgkmcnt(4)
	v_mfma_f32_32x32x16_bf16 v[34:49], v[82:85], v[130:133], v[34:49]
	ds_read_b64_tr_b16 v[142:143], v227 offset:39936
	ds_read_b64_tr_b16 v[144:145], v227 offset:40448
	v_exp_f32_e32 v186, v186
	v_exp_f32_e32 v187, v187
	v_cvt_pk_bf16_f32 v101, v184, v185
	s_waitcnt lgkmcnt(4)
	v_mfma_f32_32x32x16_bf16 v[34:49], v[86:89], v[134:137], v[34:49]
	ds_read_b64_tr_b16 v[114:115], v227 offset:40960
	ds_read_b64_tr_b16 v[116:117], v227 offset:41472
	s_add_u32 s58, s56, 0x20060080
	s_addc_u32 s59, s57, 0
	v_lshl_add_u64 v[228:229], v[240:241], 0, s[58:59]
	s_add_i32 m0, s6, 0x6000
	s_nop 0
	global_load_lds_dwordx4 v[228:229], off
	v_exp_f32_e32 v188, v188
	v_exp_f32_e32 v189, v189
	v_cvt_pk_bf16_f32 v102, v186, v187
	s_waitcnt lgkmcnt(4)
	v_mfma_f32_32x32x16_bf16 v[34:49], v[90:93], v[138:141], v[34:49]
	ds_read_b64_tr_b16 v[118:119], v227 offset:41984
	ds_read_b64_tr_b16 v[120:121], v227 offset:42496
	s_mov_b32 m0, s37
	v_exp_f32_e32 v190, v190
	v_exp_f32_e32 v191, v191
	v_cvt_pk_bf16_f32 v103, v188, v189
	s_waitcnt lgkmcnt(4)
	v_mfma_f32_32x32x16_bf16 v[34:49], v[94:97], v[142:145], v[34:49]
	ds_read_b64_tr_b16 v[122:123], v227 offset:43008
	ds_read_b64_tr_b16 v[124:125], v227 offset:43520
	v_exp_f32_e32 v192, v192
	v_exp_f32_e32 v193, v193
	v_cvt_pk_bf16_f32 v104, v190, v191
	s_waitcnt lgkmcnt(4)
	v_mfma_f32_32x32x16_bf16 v[18:33], v[82:85], v[114:117], v[18:33]
	ds_read_b64_tr_b16 v[126:127], v227 offset:44032
	ds_read_b64_tr_b16 v[128:129], v227 offset:44544
	v_exp_f32_e32 v194, v194
	v_exp_f32_e32 v195, v195
	v_cvt_pk_bf16_f32 v105, v192, v193
	s_waitcnt lgkmcnt(4)
	v_mfma_f32_32x32x16_bf16 v[18:33], v[86:89], v[118:121], v[18:33]
	ds_read_b64_tr_b16 v[130:131], v227 offset:45056
	ds_read_b64_tr_b16 v[132:133], v227 offset:45568
	v_exp_f32_e32 v196, v196
	v_exp_f32_e32 v197, v197
	v_cvt_pk_bf16_f32 v106, v194, v195
	s_waitcnt lgkmcnt(4)
	v_mfma_f32_32x32x16_bf16 v[18:33], v[90:93], v[122:125], v[18:33]
	ds_read_b64_tr_b16 v[134:135], v227 offset:46080
	ds_read_b64_tr_b16 v[136:137], v227 offset:46592
	v_exp_f32_e32 v198, v198
	v_exp_f32_e32 v199, v199
	v_cvt_pk_bf16_f32 v107, v196, v197
	s_waitcnt lgkmcnt(4)
	v_mfma_f32_32x32x16_bf16 v[18:33], v[94:97], v[126:129], v[18:33]
	ds_read_b64_tr_b16 v[138:139], v227 offset:47104
	ds_read_b64_tr_b16 v[140:141], v227 offset:47616
	v_exp_f32_e32 v200, v200
	v_exp_f32_e32 v201, v201
	v_cvt_pk_bf16_f32 v108, v198, v199
	s_waitcnt lgkmcnt(4)
	v_mfma_f32_32x32x16_bf16 v[2:17], v[82:85], v[130:133], v[2:17]
	ds_read_b64_tr_b16 v[142:143], v227 offset:48128
	ds_read_b64_tr_b16 v[144:145], v227 offset:48640
	v_exp_f32_e32 v202, v202
	v_exp_f32_e32 v203, v203
	v_cvt_pk_bf16_f32 v109, v200, v201
	s_waitcnt lgkmcnt(4)
	v_mfma_f32_32x32x16_bf16 v[2:17], v[86:89], v[134:137], v[2:17]
	ds_read_b64_tr_b16 v[114:115], v227 offset:49152
	ds_read_b64_tr_b16 v[116:117], v227 offset:49664
	v_exp_f32_e32 v204, v204
	v_exp_f32_e32 v205, v205
	v_cvt_pk_bf16_f32 v110, v202, v203
	s_waitcnt lgkmcnt(4)
	v_mfma_f32_32x32x16_bf16 v[2:17], v[90:93], v[138:141], v[2:17]
	ds_read_b64_tr_b16 v[118:119], v227 offset:50176
	ds_read_b64_tr_b16 v[120:121], v227 offset:50688
	v_exp_f32_e32 v206, v206
	v_exp_f32_e32 v207, v207
	v_cvt_pk_bf16_f32 v111, v204, v205
	s_waitcnt lgkmcnt(4)
	v_mfma_f32_32x32x16_bf16 v[2:17], v[94:97], v[142:145], v[2:17]
	ds_read_b64_tr_b16 v[122:123], v227 offset:51200
	ds_read_b64_tr_b16 v[124:125], v227 offset:51712
	v_exp_f32_e32 v208, v208
	v_exp_f32_e32 v209, v209
	v_cvt_pk_bf16_f32 v112, v206, v207
	s_waitcnt lgkmcnt(4)
	v_mfma_f32_32x32x16_bf16 v[50:65], v[98:101], v[114:117], v[50:65]
	ds_read_b64_tr_b16 v[126:127], v227 offset:52224
	ds_read_b64_tr_b16 v[128:129], v227 offset:52736
	v_cvt_pk_bf16_f32 v113, v208, v209
	v_add_f32_e32 v226, v162, v146
	v_add_f32_e32 v0, v194, v178
	s_waitcnt lgkmcnt(4)
	v_mfma_f32_32x32x16_bf16 v[50:65], v[102:105], v[118:121], v[50:65]
	ds_read_b64_tr_b16 v[130:131], v227 offset:53248
	ds_read_b64_tr_b16 v[132:133], v227 offset:53760
	v_add_f32_e32 v228, v163, v147
	v_add_f32_e32 v229, v195, v179
	v_add_f32_e32 v226, v228, v226
	v_add_f32_e32 v0, v229, v0
	s_waitcnt lgkmcnt(4)
	v_mfma_f32_32x32x16_bf16 v[50:65], v[106:109], v[122:125], v[50:65]
	ds_read_b64_tr_b16 v[134:135], v227 offset:54272
	ds_read_b64_tr_b16 v[136:137], v227 offset:54784
	v_add_f32_e32 v228, v164, v148
	v_add_f32_e32 v229, v196, v180
	v_add_f32_e32 v226, v228, v226
	v_add_f32_e32 v0, v229, v0
	s_waitcnt lgkmcnt(4)
	v_mfma_f32_32x32x16_bf16 v[50:65], v[110:113], v[126:129], v[50:65]
	ds_read_b64_tr_b16 v[138:139], v227 offset:55296
	ds_read_b64_tr_b16 v[140:141], v227 offset:55808
	v_add_f32_e32 v228, v165, v149
	v_add_f32_e32 v229, v197, v181
	v_add_f32_e32 v226, v228, v226
	v_add_f32_e32 v0, v229, v0
	s_waitcnt lgkmcnt(4)
	v_mfma_f32_32x32x16_bf16 v[34:49], v[98:101], v[130:133], v[34:49]
	ds_read_b64_tr_b16 v[142:143], v227 offset:56320
	ds_read_b64_tr_b16 v[144:145], v227 offset:56832
	v_add_f32_e32 v228, v166, v150
	v_add_f32_e32 v229, v198, v182
	v_add_f32_e32 v226, v228, v226
	v_add_f32_e32 v0, v229, v0
	s_waitcnt lgkmcnt(4)
	v_mfma_f32_32x32x16_bf16 v[34:49], v[102:105], v[134:137], v[34:49]
	ds_read_b64_tr_b16 v[114:115], v227 offset:57344
	ds_read_b64_tr_b16 v[116:117], v227 offset:57856
	v_add_f32_e32 v228, v167, v151
	v_add_f32_e32 v229, v199, v183
	v_add_f32_e32 v226, v228, v226
	v_add_f32_e32 v0, v229, v0
	s_waitcnt lgkmcnt(4)
	v_mfma_f32_32x32x16_bf16 v[34:49], v[106:109], v[138:141], v[34:49]
	ds_read_b64_tr_b16 v[118:119], v227 offset:58368
	ds_read_b64_tr_b16 v[120:121], v227 offset:58880
	v_add_f32_e32 v228, v168, v152
	v_add_f32_e32 v229, v200, v184
	v_add_f32_e32 v226, v228, v226
	v_add_f32_e32 v0, v229, v0
	s_waitcnt lgkmcnt(4)
	v_mfma_f32_32x32x16_bf16 v[34:49], v[110:113], v[142:145], v[34:49]
	ds_read_b64_tr_b16 v[122:123], v227 offset:59392
	ds_read_b64_tr_b16 v[124:125], v227 offset:59904
	v_add_f32_e32 v228, v169, v153
	v_add_f32_e32 v229, v201, v185
	v_add_f32_e32 v226, v228, v226
	v_add_f32_e32 v0, v229, v0
	s_waitcnt lgkmcnt(4)
	v_mfma_f32_32x32x16_bf16 v[18:33], v[98:101], v[114:117], v[18:33]
	ds_read_b64_tr_b16 v[126:127], v227 offset:60416
	ds_read_b64_tr_b16 v[128:129], v227 offset:60928
	v_add_f32_e32 v228, v170, v154
	v_add_f32_e32 v229, v202, v186
	v_add_f32_e32 v226, v228, v226
	v_add_f32_e32 v0, v229, v0
	s_waitcnt lgkmcnt(4)
	v_mfma_f32_32x32x16_bf16 v[18:33], v[102:105], v[118:121], v[18:33]
	ds_read_b64_tr_b16 v[130:131], v227 offset:61440
	ds_read_b64_tr_b16 v[132:133], v227 offset:61952
	v_add_f32_e32 v228, v171, v155
	v_add_f32_e32 v229, v203, v187
	v_add_f32_e32 v226, v228, v226
	v_add_f32_e32 v0, v229, v0
	s_waitcnt lgkmcnt(4)
	v_mfma_f32_32x32x16_bf16 v[18:33], v[106:109], v[122:125], v[18:33]
	ds_read_b64_tr_b16 v[134:135], v227 offset:62464
	ds_read_b64_tr_b16 v[136:137], v227 offset:62976
	v_add_f32_e32 v228, v172, v156
	v_add_f32_e32 v229, v204, v188
	v_add_f32_e32 v226, v228, v226
	v_add_f32_e32 v0, v229, v0
	s_waitcnt lgkmcnt(4)
	v_mfma_f32_32x32x16_bf16 v[18:33], v[110:113], v[126:129], v[18:33]
	ds_read_b64_tr_b16 v[138:139], v227 offset:63488
	ds_read_b64_tr_b16 v[140:141], v227 offset:64000
	v_add_f32_e32 v228, v173, v157
	v_add_f32_e32 v229, v205, v189
	v_add_f32_e32 v226, v228, v226
	v_add_f32_e32 v0, v229, v0
	s_waitcnt lgkmcnt(4)
	v_mfma_f32_32x32x16_bf16 v[2:17], v[98:101], v[130:133], v[2:17]
	ds_read_b64_tr_b16 v[142:143], v227 offset:64512
	ds_read_b64_tr_b16 v[144:145], v227 offset:65024
	v_add_f32_e32 v228, v174, v158
	v_add_f32_e32 v229, v206, v190
	v_add_f32_e32 v226, v228, v226
	v_add_f32_e32 v0, v229, v0
	s_waitcnt lgkmcnt(4)
	v_mfma_f32_32x32x16_bf16 v[2:17], v[102:105], v[134:137], v[2:17]
	v_add_f32_e32 v228, v175, v159
	v_add_f32_e32 v229, v207, v191
	v_add_f32_e32 v226, v228, v226
	v_add_f32_e32 v0, v229, v0
	s_waitcnt lgkmcnt(2)
	v_mfma_f32_32x32x16_bf16 v[2:17], v[106:109], v[138:141], v[2:17]
	v_add_f32_e32 v228, v176, v160
	v_add_f32_e32 v229, v208, v192
	v_add_f32_e32 v226, v228, v226
	v_add_f32_e32 v0, v229, v0
	s_waitcnt lgkmcnt(0)
	v_mfma_f32_32x32x16_bf16 v[2:17], v[110:113], v[142:145], v[2:17]
	v_add_f32_e32 v228, v177, v161
	v_add_f32_e32 v229, v209, v193
	v_add_f32_e32 v226, v228, v226
	v_add_f32_e32 v0, v229, v0
	v_add_f32_e32 v226, v226, v0
	v_add_f32_e32 v0, v237, v226
	s_branch .Lattn_pv_done
.Lattn_pv_nodma:
	v_lshl_add_u32 v227, s36, 15, v230
	ds_read_b64_tr_b16 v[114:115], v227 offset:32768
	ds_read_b64_tr_b16 v[116:117], v227 offset:33280
	ds_read_b64_tr_b16 v[118:119], v227 offset:33792
	ds_read_b64_tr_b16 v[120:121], v227 offset:34304
	ds_read_b64_tr_b16 v[122:123], v227 offset:34816
	ds_read_b64_tr_b16 v[124:125], v227 offset:35328
	v_exp_f32_e32 v146, v146
	v_exp_f32_e32 v147, v147
	v_exp_f32_e32 v162, v162
	v_exp_f32_e32 v163, v163
	v_exp_f32_e32 v148, v148
	v_exp_f32_e32 v149, v149
	v_exp_f32_e32 v164, v164
	v_exp_f32_e32 v165, v165
	v_cvt_pk_bf16_f32 v82, v146, v147
	v_cvt_pk_bf16_f32 v90, v162, v163
	v_exp_f32_e32 v150, v150
	v_exp_f32_e32 v151, v151
	v_exp_f32_e32 v166, v166
	v_exp_f32_e32 v167, v167
	v_cvt_pk_bf16_f32 v83, v148, v149
	v_cvt_pk_bf16_f32 v91, v164, v165
	v_exp_f32_e32 v152, v152
	v_exp_f32_e32 v153, v153
	v_exp_f32_e32 v168, v168
	v_exp_f32_e32 v169, v169
	v_cvt_pk_bf16_f32 v84, v150, v151
	v_cvt_pk_bf16_f32 v92, v166, v167
	v_exp_f32_e32 v154, v154
	v_exp_f32_e32 v155, v155
	v_exp_f32_e32 v170, v170
	v_exp_f32_e32 v171, v171
	v_cvt_pk_bf16_f32 v85, v152, v153
	v_cvt_pk_bf16_f32 v93, v168, v169
	v_exp_f32_e32 v156, v156
	v_exp_f32_e32 v157, v157
	v_exp_f32_e32 v172, v172
	v_exp_f32_e32 v173, v173
	v_cvt_pk_bf16_f32 v86, v154, v155
	v_cvt_pk_bf16_f32 v94, v170, v171
	v_exp_f32_e32 v158, v158
	v_exp_f32_e32 v159, v159
	v_exp_f32_e32 v174, v174
	v_exp_f32_e32 v175, v175
	v_cvt_pk_bf16_f32 v87, v156, v157
	v_cvt_pk_bf16_f32 v95, v172, v173
	v_exp_f32_e32 v160, v160
	v_exp_f32_e32 v161, v161
	v_exp_f32_e32 v176, v176
	v_exp_f32_e32 v177, v177
	v_cvt_pk_bf16_f32 v88, v158, v159
	v_cvt_pk_bf16_f32 v96, v174, v175
	s_nop 0
	v_cvt_pk_bf16_f32 v89, v160, v161
	v_cvt_pk_bf16_f32 v97, v176, v177
	s_waitcnt lgkmcnt(4)
	v_mfma_f32_32x32x16_bf16 v[50:65], v[82:85], v[114:117], v[50:65]
	ds_read_b64_tr_b16 v[126:127], v227 offset:35840
	ds_read_b64_tr_b16 v[128:129], v227 offset:36352
	v_exp_f32_e32 v178, v178
	v_exp_f32_e32 v179, v179
	s_waitcnt lgkmcnt(4)
	v_mfma_f32_32x32x16_bf16 v[50:65], v[86:89], v[118:121], v[50:65]
	ds_read_b64_tr_b16 v[130:131], v227 offset:36864
	ds_read_b64_tr_b16 v[132:133], v227 offset:37376
	v_exp_f32_e32 v180, v180
	v_exp_f32_e32 v181, v181
	v_cvt_pk_bf16_f32 v98, v178, v179
	s_waitcnt lgkmcnt(4)
	v_mfma_f32_32x32x16_bf16 v[50:65], v[90:93], v[122:125], v[50:65]
	ds_read_b64_tr_b16 v[134:135], v227 offset:37888
	ds_read_b64_tr_b16 v[136:137], v227 offset:38400
	v_exp_f32_e32 v182, v182
	v_exp_f32_e32 v183, v183
	v_cvt_pk_bf16_f32 v99, v180, v181
	s_waitcnt lgkmcnt(4)
	v_mfma_f32_32x32x16_bf16 v[50:65], v[94:97], v[126:129], v[50:65]
	ds_read_b64_tr_b16 v[138:139], v227 offset:38912
	ds_read_b64_tr_b16 v[140:141], v227 offset:39424
	v_exp_f32_e32 v184, v184
	v_exp_f32_e32 v185, v185
	v_cvt_pk_bf16_f32 v100, v182, v183
	s_waitcnt lgkmcnt(4)
	v_mfma_f32_32x32x16_bf16 v[34:49], v[82:85], v[130:133], v[34:49]
	ds_read_b64_tr_b16 v[142:143], v227 offset:39936
	ds_read_b64_tr_b16 v[144:145], v227 offset:40448
	v_exp_f32_e32 v186, v186
	v_exp_f32_e32 v187, v187
	v_cvt_pk_bf16_f32 v101, v184, v185
	s_waitcnt lgkmcnt(4)
	v_mfma_f32_32x32x16_bf16 v[34:49], v[86:89], v[134:137], v[34:49]
	ds_read_b64_tr_b16 v[114:115], v227 offset:40960
	ds_read_b64_tr_b16 v[116:117], v227 offset:41472
	v_exp_f32_e32 v188, v188
	v_exp_f32_e32 v189, v189
	v_cvt_pk_bf16_f32 v102, v186, v187
	s_waitcnt lgkmcnt(4)
	v_mfma_f32_32x32x16_bf16 v[34:49], v[90:93], v[138:141], v[34:49]
	ds_read_b64_tr_b16 v[118:119], v227 offset:41984
	ds_read_b64_tr_b16 v[120:121], v227 offset:42496
	v_exp_f32_e32 v190, v190
	v_exp_f32_e32 v191, v191
	v_cvt_pk_bf16_f32 v103, v188, v189
	s_waitcnt lgkmcnt(4)
	v_mfma_f32_32x32x16_bf16 v[34:49], v[94:97], v[142:145], v[34:49]
	ds_read_b64_tr_b16 v[122:123], v227 offset:43008
	ds_read_b64_tr_b16 v[124:125], v227 offset:43520
	v_exp_f32_e32 v192, v192
	v_exp_f32_e32 v193, v193
	v_cvt_pk_bf16_f32 v104, v190, v191
	s_waitcnt lgkmcnt(4)
	v_mfma_f32_32x32x16_bf16 v[18:33], v[82:85], v[114:117], v[18:33]
	ds_read_b64_tr_b16 v[126:127], v227 offset:44032
	ds_read_b64_tr_b16 v[128:129], v227 offset:44544
	v_exp_f32_e32 v194, v194
	v_exp_f32_e32 v195, v195
	v_cvt_pk_bf16_f32 v105, v192, v193
	s_waitcnt lgkmcnt(4)
	v_mfma_f32_32x32x16_bf16 v[18:33], v[86:89], v[118:121], v[18:33]
	ds_read_b64_tr_b16 v[130:131], v227 offset:45056
	ds_read_b64_tr_b16 v[132:133], v227 offset:45568
	v_exp_f32_e32 v196, v196
	v_exp_f32_e32 v197, v197
	v_cvt_pk_bf16_f32 v106, v194, v195
	s_waitcnt lgkmcnt(4)
	v_mfma_f32_32x32x16_bf16 v[18:33], v[90:93], v[122:125], v[18:33]
	ds_read_b64_tr_b16 v[134:135], v227 offset:46080
	ds_read_b64_tr_b16 v[136:137], v227 offset:46592
	v_exp_f32_e32 v198, v198
	v_exp_f32_e32 v199, v199
	v_cvt_pk_bf16_f32 v107, v196, v197
	s_waitcnt lgkmcnt(4)
	v_mfma_f32_32x32x16_bf16 v[18:33], v[94:97], v[126:129], v[18:33]
	ds_read_b64_tr_b16 v[138:139], v227 offset:47104
	ds_read_b64_tr_b16 v[140:141], v227 offset:47616
	v_exp_f32_e32 v200, v200
	v_exp_f32_e32 v201, v201
	v_cvt_pk_bf16_f32 v108, v198, v199
	s_waitcnt lgkmcnt(4)
	v_mfma_f32_32x32x16_bf16 v[2:17], v[82:85], v[130:133], v[2:17]
	ds_read_b64_tr_b16 v[142:143], v227 offset:48128
	ds_read_b64_tr_b16 v[144:145], v227 offset:48640
	v_exp_f32_e32 v202, v202
	v_exp_f32_e32 v203, v203
	v_cvt_pk_bf16_f32 v109, v200, v201
	s_waitcnt lgkmcnt(4)
	v_mfma_f32_32x32x16_bf16 v[2:17], v[86:89], v[134:137], v[2:17]
	ds_read_b64_tr_b16 v[114:115], v227 offset:49152
	ds_read_b64_tr_b16 v[116:117], v227 offset:49664
	v_exp_f32_e32 v204, v204
	v_exp_f32_e32 v205, v205
	v_cvt_pk_bf16_f32 v110, v202, v203
	s_waitcnt lgkmcnt(4)
	v_mfma_f32_32x32x16_bf16 v[2:17], v[90:93], v[138:141], v[2:17]
	ds_read_b64_tr_b16 v[118:119], v227 offset:50176
	ds_read_b64_tr_b16 v[120:121], v227 offset:50688
	v_exp_f32_e32 v206, v206
	v_exp_f32_e32 v207, v207
	v_cvt_pk_bf16_f32 v111, v204, v205
	s_waitcnt lgkmcnt(4)
	v_mfma_f32_32x32x16_bf16 v[2:17], v[94:97], v[142:145], v[2:17]
	ds_read_b64_tr_b16 v[122:123], v227 offset:51200
	ds_read_b64_tr_b16 v[124:125], v227 offset:51712
	v_exp_f32_e32 v208, v208
	v_exp_f32_e32 v209, v209
	v_cvt_pk_bf16_f32 v112, v206, v207
	s_waitcnt lgkmcnt(4)
	v_mfma_f32_32x32x16_bf16 v[50:65], v[98:101], v[114:117], v[50:65]
	ds_read_b64_tr_b16 v[126:127], v227 offset:52224
	ds_read_b64_tr_b16 v[128:129], v227 offset:52736
	v_cvt_pk_bf16_f32 v113, v208, v209
	v_add_f32_e32 v226, v162, v146
	v_add_f32_e32 v0, v194, v178
	s_waitcnt lgkmcnt(4)
	v_mfma_f32_32x32x16_bf16 v[50:65], v[102:105], v[118:121], v[50:65]
	ds_read_b64_tr_b16 v[130:131], v227 offset:53248
	ds_read_b64_tr_b16 v[132:133], v227 offset:53760
	v_add_f32_e32 v228, v163, v147
	v_add_f32_e32 v229, v195, v179
	v_add_f32_e32 v226, v228, v226
	v_add_f32_e32 v0, v229, v0
	s_waitcnt lgkmcnt(4)
	v_mfma_f32_32x32x16_bf16 v[50:65], v[106:109], v[122:125], v[50:65]
	ds_read_b64_tr_b16 v[134:135], v227 offset:54272
	ds_read_b64_tr_b16 v[136:137], v227 offset:54784
	v_add_f32_e32 v228, v164, v148
	v_add_f32_e32 v229, v196, v180
	v_add_f32_e32 v226, v228, v226
	v_add_f32_e32 v0, v229, v0
	s_waitcnt lgkmcnt(4)
	v_mfma_f32_32x32x16_bf16 v[50:65], v[110:113], v[126:129], v[50:65]
	ds_read_b64_tr_b16 v[138:139], v227 offset:55296
	ds_read_b64_tr_b16 v[140:141], v227 offset:55808
	v_add_f32_e32 v228, v165, v149
	v_add_f32_e32 v229, v197, v181
	v_add_f32_e32 v226, v228, v226
	v_add_f32_e32 v0, v229, v0
	s_waitcnt lgkmcnt(4)
	v_mfma_f32_32x32x16_bf16 v[34:49], v[98:101], v[130:133], v[34:49]
	ds_read_b64_tr_b16 v[142:143], v227 offset:56320
	ds_read_b64_tr_b16 v[144:145], v227 offset:56832
	v_add_f32_e32 v228, v166, v150
	v_add_f32_e32 v229, v198, v182
	v_add_f32_e32 v226, v228, v226
	v_add_f32_e32 v0, v229, v0
	s_waitcnt lgkmcnt(4)
	v_mfma_f32_32x32x16_bf16 v[34:49], v[102:105], v[134:137], v[34:49]
	ds_read_b64_tr_b16 v[114:115], v227 offset:57344
	ds_read_b64_tr_b16 v[116:117], v227 offset:57856
	v_add_f32_e32 v228, v167, v151
	v_add_f32_e32 v229, v199, v183
	v_add_f32_e32 v226, v228, v226
	v_add_f32_e32 v0, v229, v0
	s_waitcnt lgkmcnt(4)
	v_mfma_f32_32x32x16_bf16 v[34:49], v[106:109], v[138:141], v[34:49]
	ds_read_b64_tr_b16 v[118:119], v227 offset:58368
	ds_read_b64_tr_b16 v[120:121], v227 offset:58880
	v_add_f32_e32 v228, v168, v152
	v_add_f32_e32 v229, v200, v184
	v_add_f32_e32 v226, v228, v226
	v_add_f32_e32 v0, v229, v0
	s_waitcnt lgkmcnt(4)
	v_mfma_f32_32x32x16_bf16 v[34:49], v[110:113], v[142:145], v[34:49]
	ds_read_b64_tr_b16 v[122:123], v227 offset:59392
	ds_read_b64_tr_b16 v[124:125], v227 offset:59904
	v_add_f32_e32 v228, v169, v153
	v_add_f32_e32 v229, v201, v185
	v_add_f32_e32 v226, v228, v226
	v_add_f32_e32 v0, v229, v0
	s_waitcnt lgkmcnt(4)
	v_mfma_f32_32x32x16_bf16 v[18:33], v[98:101], v[114:117], v[18:33]
	ds_read_b64_tr_b16 v[126:127], v227 offset:60416
	ds_read_b64_tr_b16 v[128:129], v227 offset:60928
	v_add_f32_e32 v228, v170, v154
	v_add_f32_e32 v229, v202, v186
	v_add_f32_e32 v226, v228, v226
	v_add_f32_e32 v0, v229, v0
	s_waitcnt lgkmcnt(4)
	v_mfma_f32_32x32x16_bf16 v[18:33], v[102:105], v[118:121], v[18:33]
	ds_read_b64_tr_b16 v[130:131], v227 offset:61440
	ds_read_b64_tr_b16 v[132:133], v227 offset:61952
	v_add_f32_e32 v228, v171, v155
	v_add_f32_e32 v229, v203, v187
	v_add_f32_e32 v226, v228, v226
	v_add_f32_e32 v0, v229, v0
	s_waitcnt lgkmcnt(4)
	v_mfma_f32_32x32x16_bf16 v[18:33], v[106:109], v[122:125], v[18:33]
	ds_read_b64_tr_b16 v[134:135], v227 offset:62464
	ds_read_b64_tr_b16 v[136:137], v227 offset:62976
	v_add_f32_e32 v228, v172, v156
	v_add_f32_e32 v229, v204, v188
	v_add_f32_e32 v226, v228, v226
	v_add_f32_e32 v0, v229, v0
	s_waitcnt lgkmcnt(4)
	v_mfma_f32_32x32x16_bf16 v[18:33], v[110:113], v[126:129], v[18:33]
	ds_read_b64_tr_b16 v[138:139], v227 offset:63488
	ds_read_b64_tr_b16 v[140:141], v227 offset:64000
	v_add_f32_e32 v228, v173, v157
	v_add_f32_e32 v229, v205, v189
	v_add_f32_e32 v226, v228, v226
	v_add_f32_e32 v0, v229, v0
	s_waitcnt lgkmcnt(4)
	v_mfma_f32_32x32x16_bf16 v[2:17], v[98:101], v[130:133], v[2:17]
	ds_read_b64_tr_b16 v[142:143], v227 offset:64512
	ds_read_b64_tr_b16 v[144:145], v227 offset:65024
	v_add_f32_e32 v228, v174, v158
	v_add_f32_e32 v229, v206, v190
	v_add_f32_e32 v226, v228, v226
	v_add_f32_e32 v0, v229, v0
	s_waitcnt lgkmcnt(4)
	v_mfma_f32_32x32x16_bf16 v[2:17], v[102:105], v[134:137], v[2:17]
	v_add_f32_e32 v228, v175, v159
	v_add_f32_e32 v229, v207, v191
	v_add_f32_e32 v226, v228, v226
	v_add_f32_e32 v0, v229, v0
	s_waitcnt lgkmcnt(2)
	v_mfma_f32_32x32x16_bf16 v[2:17], v[106:109], v[138:141], v[2:17]
	v_add_f32_e32 v228, v176, v160
	v_add_f32_e32 v229, v208, v192
	v_add_f32_e32 v226, v228, v226
	v_add_f32_e32 v0, v229, v0
	s_waitcnt lgkmcnt(0)
	v_mfma_f32_32x32x16_bf16 v[2:17], v[110:113], v[142:145], v[2:17]
	v_add_f32_e32 v228, v177, v161
	v_add_f32_e32 v229, v209, v193
	v_add_f32_e32 v226, v228, v226
	v_add_f32_e32 v0, v229, v0
	v_add_f32_e32 v226, v226, v0
	v_add_f32_e32 v0, v237, v226
